# speedup vs baseline: 1.0116x; 1.0116x over previous
; #define LAS __attribute__((address_space(3)))
; __device__ __forceinline__ void pool_units(LAS unsigned char* lds, const bf16* Z, const float* state, const bf16* Wpt, const float* pscale, bf16* MIXIN, int bx, int G, int tid, int wid, int lane) {
;     LAS bf16* Ul = (LAS bf16*)lds; LAS bf16* Dl = (LAS bf16*)(lds + PL_D_OFF);
;     PRegs R;
;     int u = bx + (G >> 1); if (u >= G) u -= G;
;     if (u < NATT) pool_load(R, Z, state, u >> 2, u & 3, tid);
; #pragma unroll 1
;     for (; u < NATT; u += G) {
;         const int idx = u >> 2, g = u & 3;
;         const bool sample = idx >= 256; const int c = idx & 31; const int row0 = idx * 64; const int w = 2 << g;
;         { const int rb = tid >> 5, cgx = tid & 31;
;           *(LAS v4u*)(Ul + rb * PL_DS + cgx * 8) = R.c0; *(LAS v4u*)(Ul + (rb + 16) * PL_DS + cgx * 8) = R.c1; *(LAS v4u*)(Ul + (rb + 32) * PL_DS + cgx * 8) = R.c2;
;           *(LAS v4u*)(Ul + (rb + 48) * PL_DS + cgx * 8) = R.c3; if (rb + 64 < 79) *(LAS v4u*)(Ul + (rb + 64) * PL_DS + cgx * 8) = R.c4; }
;         const int fr = lane & 15, fq = lane >> 4;
;         const bf16* wb = Wpt + (size_t)g * 65536 + (size_t)(32 * wid + fr) * 256 + fq * 8;
.LBB0_120:
	s_andn2_b64 vcc, exec, s[28:29]
	s_cbranch_vccnz .LBB0_170
	s_and_b64 s[12:13], s[18:19], exec
	s_cselect_b32 s12, 0x1000, 0
	v_lshl_add_u32 v106, v107, 1, 0
	s_add_u32 s28, s26, s12
	v_mad_u64_u32 v[108:109], s[12:13], v104, s91, v[106:107]
	v_readlane_b32 s12, v240, 1
	s_addc_u32 s29, s27, 0
	v_and_b32_e32 v109, 15, v180
	s_lshl_b32 s12, s12, 5
	s_waitcnt vmcnt(0)
	v_or_b32_e32 v2, s12, v109
	v_ashrrev_i32_e32 v3, 31, v2
	v_lshlrev_b64 v[2:3], 9, v[2:3]
	v_lshl_add_u64 v[2:3], s[14:15], 0, v[2:3]
	v_and_b32_e32 v0, 48, v206
	v_lshl_add_u64 v[2:3], v[2:3], 0, v[0:1]
	s_mov_b64 s[26:27], 0x5400000
	s_ashr_i32 s13, s12, 31
	v_lshl_add_u64 v[110:111], v[2:3], 0, s[26:27]
	s_lshl_b64 s[26:27], s[12:13], 2
	s_movk_i32 s13, 0xffee
	v_lshrrev_b32_e32 v2, 2, v206
	v_cmp_lt_i32_e64 s[30:31], s13, v104
	s_movk_i32 s13, 0xffef
	s_add_u32 s26, s28, s26
	v_cmp_gt_i32_e64 s[44:45], s13, v104
	s_movk_i32 s13, 0xffde
	v_and_or_b32 v159, v2, 12, s12
	s_movk_i32 s12, 0x840
	s_addc_u32 s27, s29, s27
	v_cmp_lt_i32_e64 s[34:35], s13, v104
	s_movk_i32 s13, 0xffdf
	v_lshlrev_b32_e32 v158, 2, v104
	v_mul_lo_u32 v2, v104, s12
	s_add_i32 s12, s2, s3
	v_cmp_gt_i32_e64 s[46:47], s13, v104
	s_movk_i32 s13, 0xffce
	v_or_b32_e32 v160, 1, v158
	v_or_b32_e32 v17, 48, v206
	s_add_i32 s12, s12, s5
	v_lshl_add_u64 v[112:113], s[26:27], 0, v[0:1]
	v_add_u32_e32 v114, 16, v104
	v_add_u32_e32 v116, 32, v104
	v_add_u32_e32 v118, 48, v104
	v_cmp_lt_i32_e64 s[36:37], s13, v104
	s_movk_i32 s13, 0xffcf
	v_add_u32_e32 v120, 64, v104
	v_add_u32_e32 v0, 0, v0
	v_mul_lo_u32 v3, v160, s91
	v_mul_u32_u24_e32 v16, 0x210, v109
	v_mul_u32_u24_e32 v17, 0x210, v17
	s_sub_i32 s5, s12, s11
	v_cmp_gt_i32_e64 s[40:41], 15, v104
	v_cmp_lt_i32_e64 s[26:27], 14, v104
	v_ashrrev_i32_e32 v105, 31, v104
	v_add_u32_e32 v152, -15, v104
	v_cmp_lt_i32_e64 s[28:29], -2, v104
	v_cmp_gt_i32_e64 s[42:43], -1, v104
	v_ashrrev_i32_e32 v115, 31, v114
	v_add_u32_e32 v153, 1, v104
	v_ashrrev_i32_e32 v117, 31, v116
	v_add_u32_e32 v154, 17, v104
	v_ashrrev_i32_e32 v119, 31, v118
	v_add_u32_e32 v156, 33, v104
	v_cmp_gt_i32_e64 s[48:49], s13, v104
	v_ashrrev_i32_e32 v121, 31, v120
	v_add_u32_e32 v157, 49, v104
	v_or_b32_e32 v161, 2, v158
	v_or_b32_e32 v162, 3, v158
	s_lshl_b32 s11, s5, 8
	s_lshl_b32 s60, s3, 8
	v_add_u32_e32 v163, v106, v2
	v_add_u32_e32 v164, v106, v3
	v_add_u32_e32 v165, v0, v16
	v_add_u32_e32 v166, v0, v17
	v_lshrrev_b32_e32 v242, 6, v180
	v_and_b32_e32 v243, 63, v180
	v_mul_u32_u24_e32 v242, 0x1c00, v242
	v_lshl_add_u32 v242, v243, 4, v242
	v_add_u32_e32 v242, 0x12c00, v242
	s_branch .LBB0_125

; #define LAS __attribute__((address_space(3)))
; __device__ __forceinline__ void pool_units(LAS unsigned char* lds, const bf16* Z, const float* state, const bf16* Wpt, const float* pscale, bf16* MIXIN, int bx, int G, int tid, int wid, int lane) {
;     ...
;         { const int rb = tid >> 5, cgx = tid & 31;
;           *(LAS v4u*)(Ul + rb * PL_DS + cgx * 8) = R.c0; *(LAS v4u*)(Ul + (rb + 16) * PL_DS + cgx * 8) = R.c1; *(LAS v4u*)(Ul + (rb + 32) * PL_DS + cgx * 8) = R.c2;
;           *(LAS v4u*)(Ul + (rb + 48) * PL_DS + cgx * 8) = R.c3; if (rb + 64 < 79) *(LAS v4u*)(Ul + (rb + 64) * PL_DS + cgx * 8) = R.c4; }
;         const int fr = lane & 15, fq = lane >> 4;
;         const bf16* wb = Wpt + (size_t)g * 65536 + (size_t)(32 * wid + fr) * 256 + fq * 8;
;         bf16x8 wa[8][2];
; #pragma unroll
;         for (int ks = 0; ks < 8; ++ks)
; #pragma unroll
;             for (int nt = 0; nt < 2; ++nt) wa[ks][nt] = *(const bf16x8*)(wb + nt * 16 * 256 + ks * 32);
;         f32x4 psc[2];
; #pragma unroll
;         for (int nt = 0; nt < 2; ++nt) psc[nt] = *(const f32x4*)(pscale + g * 256 + 32 * wid + 16 * nt + fq * 4);
;         __syncthreads();
;         if (u + G < NATT) pool_load(R, Z, state, (u + G) >> 2, (u + G) & 3, tid);
.Lpool_head2:
	s_waitcnt vmcnt(0)
	ds_write_b128 v108, v[4:7]
	ds_write_b128 v108, v[8:11] offset:8448
	ds_write_b128 v108, v[12:15] offset:16896
	ds_write_b128 v108, v[20:23] offset:25344
	s_and_saveexec_b64 s[38:39], s[40:41]
	ds_write_b128 v108, v[52:55] offset:33792
	s_or_b64 exec, exec, s[38:39]
	s_and_b32 s5, s4, 3
	s_lshl_b32 s88, s5, 17
	v_lshl_add_u64 v[2:3], v[110:111], 0, s[88:89]
	v_add_co_u32_e32 v16, vcc, 0x2000, v2
	s_lshl_b32 s88, s5, 10
	s_nop 0
	v_addc_co_u32_e32 v17, vcc, 0, v3, vcc
	ds_read_b128 v[48:51], v242
	ds_read_b128 v[56:59], v242 offset:1024
	ds_read_b128 v[44:47], v242 offset:2048
	ds_read_b128 v[40:43], v242 offset:3072
	ds_read_b128 v[32:35], v242 offset:4096
	ds_read_b128 v[36:39], v242 offset:5120
	ds_read_b128 v[28:31], v242 offset:6144
	v_lshl_add_u64 v[2:3], v[112:113], 0, s[88:89]
	global_load_dwordx4 v[24:27], v[2:3], off
	global_load_dwordx4 v[16:19], v[2:3], off offset:64
	s_branch .Lpool_join
.LBB0_125:
	s_waitcnt vmcnt(0)
	ds_write_b128 v108, v[4:7]
	ds_write_b128 v108, v[8:11] offset:8448
	ds_write_b128 v108, v[12:15] offset:16896
	ds_write_b128 v108, v[20:23] offset:25344
	s_and_saveexec_b64 s[38:39], s[40:41]
	ds_write_b128 v108, v[52:55] offset:33792
	s_or_b64 exec, exec, s[38:39]
	s_and_b32 s5, s4, 3
	s_lshl_b32 s88, s5, 17
	v_lshl_add_u64 v[2:3], v[110:111], 0, s[88:89]
	v_add_co_u32_e32 v16, vcc, 0x2000, v2
	s_lshl_b32 s88, s5, 10
	s_nop 0
	v_addc_co_u32_e32 v17, vcc, 0, v3, vcc
	global_load_dwordx4 v[216:219], v[2:3], off
	global_load_dwordx4 v[220:223], v[2:3], off offset:64
	global_load_dwordx4 v[224:227], v[16:17], off
	global_load_dwordx4 v[228:231], v[16:17], off offset:64
	global_load_dwordx4 v[232:235], v[2:3], off offset:128
	global_load_dwordx4 v[236:239], v[2:3], off offset:192
	global_load_dwordx4 v[244:247], v[16:17], off offset:128
	global_load_dwordx4 v[248:251], v[16:17], off offset:192
	global_load_dwordx4 v[252:255], v[2:3], off offset:256
	global_load_dwordx4 v[48:51], v[2:3], off offset:320
	global_load_dwordx4 v[56:59], v[16:17], off offset:256
	global_load_dwordx4 v[44:47], v[16:17], off offset:320
	global_load_dwordx4 v[40:43], v[2:3], off offset:384
	global_load_dwordx4 v[32:35], v[2:3], off offset:448
	global_load_dwordx4 v[36:39], v[16:17], off offset:384
	global_load_dwordx4 v[28:31], v[16:17], off offset:448
	v_readfirstlane_b32 s38, v180
	s_lshr_b32 s38, s38, 6
	s_mulk_i32 s38, 0x1c00
	s_add_i32 s38, s38, 0x12c00
	s_add_i32 m0, s38, -320
	s_nop 0
	global_load_lds_dwordx4 v[2:3], off offset:320
	s_add_i32 m0, s38, 768
	s_nop 0
	global_load_lds_dwordx4 v[16:17], off offset:256
	s_add_i32 m0, s38, 1728
	s_nop 0
	global_load_lds_dwordx4 v[16:17], off offset:320
	s_add_i32 m0, s38, 2688
	s_nop 0
	global_load_lds_dwordx4 v[2:3], off offset:384
	s_add_i32 m0, s38, 3648
	s_nop 0
	global_load_lds_dwordx4 v[2:3], off offset:448
	s_add_i32 m0, s38, 4736
	s_nop 0
	global_load_lds_dwordx4 v[16:17], off offset:384
	s_add_i32 m0, s38, 5696
	s_nop 0
	global_load_lds_dwordx4 v[16:17], off offset:448
	v_lshl_add_u64 v[2:3], v[112:113], 0, s[88:89]
	global_load_dwordx4 v[24:27], v[2:3], off
	global_load_dwordx4 v[16:19], v[2:3], off offset:64
